# GEMM K loop: loop-control SALU updates moved from behind the last MFMA into the fragment-read shadow at the top
# speedup vs baseline: 1.0246x; 1.0080x over previous
.LBB0_246:
	s_add_i32 s10, s7, 0xffffa000
	s_cmp_lg_u32 s7, 0
	s_cselect_b32 s12, s10, 0xc000
	v_add_u32_e32 v131, s7, v150
	s_waitcnt vmcnt(6)
	s_barrier
	v_add_u32_e32 v133, s7, v149
	ds_read_b128 v[154:157], v131 offset:0
	ds_read_b128 v[158:161], v131 offset:0x400
	ds_read_b128 v[162:165], v131 offset:0x800
	ds_read_b128 v[166:169], v131 offset:0xc00
	v_add_u32_e32 v131, s12, v147
	ds_read_b128 v[170:173], v133 offset:0
	ds_read_b128 v[174:177], v133 offset:0x400
	ds_read_b128 v[178:181], v133 offset:0x800
	ds_read_b128 v[200:203], v133 offset:0xc00
	s_add_u32 s10, s8, s50
	s_addc_u32 s11, s9, s51
	v_readfirstlane_b32 s13, v131
	s_add_u32 s64, s5, s100
	s_addc_u32 s65, s6, 0
	s_add_i32 s66, s7, 0x6000
	s_cmpk_lg_u32 s7, 0xc000
	s_cselect_b32 s7, s66, 0
	s_addk_i32 s100, 0x400
	s_add_u32 s50, s50, s60
	s_addc_u32 s51, s51, 0
	s_sub_i32 s68, s13, s12
	s_lshr_b32 s68, s68, 1
	s_add_i32 s68, s68, s12
	s_addk_i32 s68, 0x4000
	s_waitcnt lgkmcnt(0)
	v_mfma_f32_16x16x32_bf16 v[126:129], v[154:157], v[170:173], v[126:129]
	ds_read_b128 v[204:207], v133 offset:0x1000
	v_mfma_f32_16x16x32_bf16 v[122:125], v[154:157], v[174:177], v[122:125]
	ds_read_b128 v[208:211], v133 offset:0x1400
	v_mfma_f32_16x16x32_bf16 v[118:121], v[154:157], v[178:181], v[118:121]
	ds_read_b128 v[212:215], v133 offset:0x1800
	v_mfma_f32_16x16x32_bf16 v[114:117], v[154:157], v[200:203], v[114:117]
	ds_read_b128 v[216:219], v133 offset:0x1c00
	s_mov_b32 m0, s13
	v_mfma_f32_16x16x32_bf16 v[110:113], v[158:161], v[170:173], v[110:113]
	global_load_lds_dwordx4 v0, s[10:11]
	v_mfma_f32_16x16x32_bf16 v[102:105], v[158:161], v[174:177], v[102:105]
	v_mfma_f32_16x16x32_bf16 v[94:97], v[158:161], v[178:181], v[94:97]
	s_add_u32 m0, s13, 0x400
	v_mfma_f32_16x16x32_bf16 v[86:89], v[158:161], v[200:203], v[86:89]
	global_load_lds_dwordx4 v130, s[10:11]
	v_mfma_f32_16x16x32_bf16 v[78:81], v[162:165], v[170:173], v[78:81]
	v_mfma_f32_16x16x32_bf16 v[70:73], v[162:165], v[174:177], v[70:73]
	s_add_u32 m0, s13, 0x800
	v_mfma_f32_16x16x32_bf16 v[62:65], v[162:165], v[178:181], v[62:65]
	global_load_lds_dwordx4 v132, s[10:11]
	v_mfma_f32_16x16x32_bf16 v[54:57], v[162:165], v[200:203], v[54:57]
	v_mfma_f32_16x16x32_bf16 v[46:49], v[166:169], v[170:173], v[46:49]
	s_add_u32 m0, s13, 0xc00
	v_mfma_f32_16x16x32_bf16 v[38:41], v[166:169], v[174:177], v[38:41]
	global_load_lds_dwordx4 v136, s[10:11]
	v_mfma_f32_16x16x32_bf16 v[30:33], v[166:169], v[178:181], v[30:33]
	v_mfma_f32_16x16x32_bf16 v[22:25], v[166:169], v[200:203], v[22:25]
	s_waitcnt lgkmcnt(0)
	v_mfma_f32_16x16x32_bf16 v[106:109], v[154:157], v[204:207], v[106:109]
	v_mfma_f32_16x16x32_bf16 v[98:101], v[154:157], v[208:211], v[98:101]
	s_mov_b32 m0, s68
	v_mfma_f32_16x16x32_bf16 v[90:93], v[154:157], v[212:215], v[90:93]
	global_load_lds_dwordx4 v138, s[64:65]
	v_mfma_f32_16x16x32_bf16 v[82:85], v[154:157], v[216:219], v[82:85]
	v_mfma_f32_16x16x32_bf16 v[74:77], v[158:161], v[204:207], v[74:77]
	v_mfma_f32_16x16x32_bf16 v[66:69], v[158:161], v[208:211], v[66:69]
	v_mfma_f32_16x16x32_bf16 v[58:61], v[158:161], v[212:215], v[58:61]
	v_mfma_f32_16x16x32_bf16 v[50:53], v[158:161], v[216:219], v[50:53]
	s_add_u32 m0, s68, 0x400
	v_mfma_f32_16x16x32_bf16 v[42:45], v[162:165], v[204:207], v[42:45]
	global_load_lds_dwordx4 v140, s[64:65]
	v_mfma_f32_16x16x32_bf16 v[34:37], v[162:165], v[208:211], v[34:37]
	v_mfma_f32_16x16x32_bf16 v[26:29], v[162:165], v[212:215], v[26:29]
	v_mfma_f32_16x16x32_bf16 v[18:21], v[162:165], v[216:219], v[18:21]
	v_mfma_f32_16x16x32_bf16 v[14:17], v[166:169], v[204:207], v[14:17]
	v_mfma_f32_16x16x32_bf16 v[10:13], v[166:169], v[208:211], v[10:13]
	v_mfma_f32_16x16x32_bf16 v[6:9], v[166:169], v[212:215], v[6:9]
	v_mfma_f32_16x16x32_bf16 v[2:5], v[166:169], v[216:219], v[2:5]
	s_cmpk_lg_i32 s100, 0x7800
	s_cbranch_scc1 .LBB0_246
	s_waitcnt vmcnt(6)
	s_barrier
	v_add_u32_e32 v0, s7, v150
	v_add_u32_e32 v140, s7, v149
	ds_read_b128 v[130:133], v0 offset:0
	ds_read_b128 v[136:139], v0 offset:0x400
	ds_read_b128 v[154:157], v0 offset:0x800
	ds_read_b128 v[158:161], v0 offset:0xc00
	ds_read_b128 v[162:165], v140 offset:0
	ds_read_b128 v[166:169], v140 offset:0x400
	ds_read_b128 v[170:173], v140 offset:0x800
	ds_read_b128 v[174:177], v140 offset:0xc00
	ds_read_b128 v[178:181], v140 offset:0x1000
	ds_read_b128 v[200:203], v140 offset:0x1400
	ds_read_b128 v[204:207], v140 offset:0x1800
	ds_read_b128 v[208:211], v140 offset:0x1c00
	s_lshl_b32 s49, s4, 8
	s_waitcnt lgkmcnt(4)
	s_nop 0
	v_mfma_f32_16x16x32_bf16 v[126:129], v[130:133], v[162:165], v[126:129]
	v_mfma_f32_16x16x32_bf16 v[118:121], v[130:133], v[170:173], v[118:121]
	v_mfma_f32_16x16x32_bf16 v[114:117], v[130:133], v[174:177], v[114:117]
	v_mfma_f32_16x16x32_bf16 v[110:113], v[136:139], v[162:165], v[110:113]
	v_mfma_f32_16x16x32_bf16 v[102:105], v[136:139], v[166:169], v[102:105]
	v_mfma_f32_16x16x32_bf16 v[94:97], v[136:139], v[170:173], v[94:97]
	v_mfma_f32_16x16x32_bf16 v[86:89], v[136:139], v[174:177], v[86:89]
	v_mfma_f32_16x16x32_bf16 v[70:73], v[154:157], v[166:169], v[70:73]
	v_mfma_f32_16x16x32_bf16 v[62:65], v[154:157], v[170:173], v[62:65]
	v_mfma_f32_16x16x32_bf16 v[54:57], v[154:157], v[174:177], v[54:57]
	v_mfma_f32_16x16x32_bf16 v[46:49], v[158:161], v[162:165], v[46:49]
	v_mfma_f32_16x16x32_bf16 v[38:41], v[158:161], v[166:169], v[38:41]
	v_mfma_f32_16x16x32_bf16 v[30:33], v[158:161], v[170:173], v[30:33]
	v_mfma_f32_16x16x32_bf16 v[22:25], v[158:161], v[174:177], v[22:25]
	v_mfma_f32_16x16x32_bf16 v[212:215], v[130:133], v[166:169], v[122:125]
	v_mfma_f32_16x16x32_bf16 v[216:219], v[154:157], v[162:165], v[78:81]
	s_waitcnt lgkmcnt(0)
	s_nop 0
	v_mfma_f32_16x16x32_bf16 v[174:177], v[136:139], v[178:181], v[74:77]
	v_mfma_f32_16x16x32_bf16 v[220:223], v[136:139], v[200:203], v[66:69]
	v_mfma_f32_16x16x32_bf16 v[224:227], v[136:139], v[204:207], v[58:61]
	v_mfma_f32_16x16x32_bf16 v[50:53], v[136:139], v[208:211], v[50:53]
	v_mfma_f32_16x16x32_bf16 v[136:139], v[154:157], v[178:181], v[42:45]
	v_mfma_f32_16x16x32_bf16 v[34:37], v[154:157], v[200:203], v[34:37]
	v_mfma_f32_16x16x32_bf16 v[6:9], v[158:161], v[204:207], v[6:9]
	v_mfma_f32_16x16x32_bf16 v[162:165], v[130:133], v[178:181], v[106:109]
	v_mfma_f32_16x16x32_bf16 v[166:169], v[130:133], v[200:203], v[98:101]
	v_mfma_f32_16x16x32_bf16 v[170:173], v[130:133], v[204:207], v[90:93]
	v_mfma_f32_16x16x32_bf16 v[130:133], v[130:133], v[208:211], v[82:85]
	v_mfma_f32_16x16x32_bf16 v[228:231], v[154:157], v[204:207], v[26:29]
	v_mfma_f32_16x16x32_bf16 v[154:157], v[154:157], v[208:211], v[18:21]
	v_mfma_f32_16x16x32_bf16 v[178:181], v[158:161], v[178:181], v[14:17]
	v_mfma_f32_16x16x32_bf16 v[200:203], v[158:161], v[200:203], v[10:13]
	v_mfma_f32_16x16x32_bf16 v[158:161], v[158:161], v[208:211], v[2:5]
	s_waitcnt vmcnt(0)
	s_barrier
	ds_read_b128 v[2:5], v151 offset:0
	ds_read_b128 v[14:17], v151 offset:0x400
	ds_read_b128 v[204:207], v151 offset:0x800
	ds_read_b128 v[208:211], v151 offset:0xc00
	ds_read_b128 v[10:13], v152 offset:0
	ds_read_b128 v[18:21], v152 offset:0x400
	ds_read_b128 v[26:29], v152 offset:0x800
	ds_read_b128 v[42:45], v152 offset:0xc00
	ds_read_b128 v[232:235], v152 offset:0x1000
	ds_read_b128 v[236:239], v152 offset:0x1400
	ds_read_b128 v[240:243], v152 offset:0x1800
	ds_read_b128 v[244:247], v152 offset:0x1c00
	s_nop 0
	s_waitcnt lgkmcnt(4)
	s_nop 0
	v_mfma_f32_16x16x32_bf16 v[122:125], v[2:5], v[10:13], v[126:129]
	v_mfma_f32_16x16x32_bf16 v[106:109], v[2:5], v[18:21], v[212:215]
	v_mfma_f32_16x16x32_bf16 v[90:93], v[2:5], v[26:29], v[118:121]
	v_mfma_f32_16x16x32_bf16 v[74:77], v[2:5], v[42:45], v[114:117]
	v_mfma_f32_16x16x32_bf16 v[126:129], v[14:17], v[10:13], v[110:113]
	v_mfma_f32_16x16x32_bf16 v[110:113], v[14:17], v[18:21], v[102:105]
	v_mfma_f32_16x16x32_bf16 v[94:97], v[14:17], v[26:29], v[94:97]
	v_mfma_f32_16x16x32_bf16 v[78:81], v[14:17], v[42:45], v[86:89]
	v_mfma_f32_16x16x32_bf16 v[114:117], v[204:207], v[10:13], v[216:219]
	v_mfma_f32_16x16x32_bf16 v[98:101], v[204:207], v[18:21], v[70:73]
	v_mfma_f32_16x16x32_bf16 v[82:85], v[204:207], v[26:29], v[62:65]
	v_mfma_f32_16x16x32_bf16 v[66:69], v[204:207], v[42:45], v[54:57]
	v_mfma_f32_16x16x32_bf16 v[118:121], v[208:211], v[10:13], v[46:49]
	v_mfma_f32_16x16x32_bf16 v[102:105], v[208:211], v[18:21], v[38:41]
	v_mfma_f32_16x16x32_bf16 v[86:89], v[208:211], v[26:29], v[30:33]
	v_mfma_f32_16x16x32_bf16 v[70:73], v[208:211], v[42:45], v[22:25]
	s_waitcnt lgkmcnt(0)
	s_nop 0
	v_mfma_f32_16x16x32_bf16 v[58:61], v[2:5], v[232:235], v[162:165]
	v_mfma_f32_16x16x32_bf16 v[42:45], v[2:5], v[236:239], v[166:169]
	v_mfma_f32_16x16x32_bf16 v[26:29], v[2:5], v[240:243], v[170:173]
	v_mfma_f32_16x16x32_bf16 v[10:13], v[2:5], v[244:247], v[130:133]
	v_mfma_f32_16x16x32_bf16 v[62:65], v[14:17], v[232:235], v[174:177]
	v_mfma_f32_16x16x32_bf16 v[46:49], v[14:17], v[236:239], v[220:223]
	v_mfma_f32_16x16x32_bf16 v[30:33], v[14:17], v[240:243], v[224:227]
	v_mfma_f32_16x16x32_bf16 v[14:17], v[14:17], v[244:247], v[50:53]
	v_mfma_f32_16x16x32_bf16 v[50:53], v[204:207], v[232:235], v[136:139]
	v_mfma_f32_16x16x32_bf16 v[34:37], v[204:207], v[236:239], v[34:37]
	v_mfma_f32_16x16x32_bf16 v[18:21], v[204:207], v[240:243], v[228:231]
	v_mfma_f32_16x16x32_bf16 v[2:5], v[204:207], v[244:247], v[154:157]
	v_mfma_f32_16x16x32_bf16 v[54:57], v[208:211], v[232:235], v[178:181]
	v_mfma_f32_16x16x32_bf16 v[38:41], v[208:211], v[236:239], v[200:203]
	v_mfma_f32_16x16x32_bf16 v[22:25], v[208:211], v[240:243], v[6:9]
	v_mfma_f32_16x16x32_bf16 v[6:9], v[208:211], v[244:247], v[158:161]
	v_mov_b32_e32 v136, v134
	s_mov_b64 s[50:51], -1
	s_and_b64 vcc, exec, s[22:23]
	s_barrier
	s_cbranch_vccz .LBB0_264
	s_and_b64 vcc, exec, s[0:1]
	s_cbranch_vccz .LBB0_250
	v_lshrrev_b32_e32 v0, 6, v136
	v_mul_lo_u32 v137, v0, s14
	v_and_b32_e32 v130, 15, v136
	v_and_or_b32 v0, v136, 48, v137
	s_movk_i32 s4, 0x90
	v_mad_u32_u24 v0, v130, s4, v0
	v_cvt_pk_bf16_f32 v130, v122, v123
	v_cvt_pk_bf16_f32 v131, v124, v125
	v_cvt_pk_bf16_f32 v132, v126, v127
	v_cvt_pk_bf16_f32 v133, v128, v129
	s_waitcnt vmcnt(0)
	ds_write_b128 v0, v[130:133]
	v_cvt_pk_bf16_f32 v130, v114, v115
	v_cvt_pk_bf16_f32 v131, v116, v117
	v_cvt_pk_bf16_f32 v132, v118, v119
	v_cvt_pk_bf16_f32 v133, v120, v121
	ds_write_b128 v0, v[130:133] offset:64
	v_cvt_pk_bf16_f32 v130, v106, v107
	v_cvt_pk_bf16_f32 v131, v108, v109
	v_cvt_pk_bf16_f32 v132, v110, v111
	v_cvt_pk_bf16_f32 v133, v112, v113
	ds_write_b128 v0, v[130:133] offset:2304
	v_cvt_pk_bf16_f32 v130, v98, v99
	v_cvt_pk_bf16_f32 v131, v100, v101
	v_cvt_pk_bf16_f32 v132, v102, v103
	v_cvt_pk_bf16_f32 v133, v104, v105
	ds_write_b128 v0, v[130:133] offset:2368
	v_cvt_pk_bf16_f32 v130, v90, v91
	v_cvt_pk_bf16_f32 v131, v92, v93
	v_cvt_pk_bf16_f32 v132, v94, v95
	v_cvt_pk_bf16_f32 v133, v96, v97
	ds_write_b128 v0, v[130:133] offset:4608
	v_cvt_pk_bf16_f32 v130, v82, v83
	v_cvt_pk_bf16_f32 v131, v84, v85
	v_cvt_pk_bf16_f32 v132, v86, v87
	v_cvt_pk_bf16_f32 v133, v88, v89
	ds_write_b128 v0, v[130:133] offset:4672
	v_cvt_pk_bf16_f32 v130, v74, v75
	v_cvt_pk_bf16_f32 v131, v76, v77
	v_cvt_pk_bf16_f32 v132, v78, v79
	v_cvt_pk_bf16_f32 v133, v80, v81
	ds_write_b128 v0, v[130:133] offset:6912
	v_cvt_pk_bf16_f32 v130, v66, v67
	v_cvt_pk_bf16_f32 v131, v68, v69
	v_cvt_pk_bf16_f32 v132, v70, v71
	v_cvt_pk_bf16_f32 v133, v72, v73
	ds_write_b128 v0, v[130:133] offset:6976
	v_cvt_pk_bf16_f32 v130, v58, v59
	v_cvt_pk_bf16_f32 v131, v60, v61
	v_cvt_pk_bf16_f32 v132, v62, v63
	v_cvt_pk_bf16_f32 v133, v64, v65
	ds_write_b128 v0, v[130:133] offset:9216
	v_cvt_pk_bf16_f32 v130, v50, v51
	v_cvt_pk_bf16_f32 v131, v52, v53
	v_cvt_pk_bf16_f32 v132, v54, v55
	v_cvt_pk_bf16_f32 v133, v56, v57
	ds_write_b128 v0, v[130:133] offset:9280
	v_cvt_pk_bf16_f32 v130, v42, v43
	v_cvt_pk_bf16_f32 v131, v44, v45
	v_cvt_pk_bf16_f32 v132, v46, v47
	v_cvt_pk_bf16_f32 v133, v48, v49
	ds_write_b128 v0, v[130:133] offset:11520
	v_cvt_pk_bf16_f32 v130, v34, v35
	v_cvt_pk_bf16_f32 v131, v36, v37
	v_cvt_pk_bf16_f32 v132, v38, v39
	v_cvt_pk_bf16_f32 v133, v40, v41
	ds_write_b128 v0, v[130:133] offset:11584
	v_cvt_pk_bf16_f32 v130, v26, v27
	v_cvt_pk_bf16_f32 v131, v28, v29
	v_cvt_pk_bf16_f32 v132, v30, v31
	v_cvt_pk_bf16_f32 v133, v32, v33
	ds_write_b128 v0, v[130:133] offset:13824
	v_cvt_pk_bf16_f32 v130, v18, v19
	v_cvt_pk_bf16_f32 v131, v20, v21
	v_cvt_pk_bf16_f32 v132, v22, v23
	v_cvt_pk_bf16_f32 v133, v24, v25
	ds_write_b128 v0, v[130:133] offset:13888
	v_cvt_pk_bf16_f32 v130, v10, v11
	v_cvt_pk_bf16_f32 v131, v12, v13
	v_cvt_pk_bf16_f32 v132, v14, v15
	v_cvt_pk_bf16_f32 v133, v16, v17
	ds_write_b128 v0, v[130:133] offset:16128
	v_cvt_pk_bf16_f32 v130, v2, v3
	v_cvt_pk_bf16_f32 v131, v4, v5
	v_cvt_pk_bf16_f32 v132, v6, v7
	v_cvt_pk_bf16_f32 v133, v8, v9
	ds_write_b128 v0, v[130:133] offset:16192
	v_and_b32_e32 v0, 0xffffff80, v136
	v_add_u32_e32 v130, s48, v0
	v_ashrrev_i32_e32 v131, 31, v130
	v_lshlrev_b64 v[130:131], 11, v[130:131]
	v_lshl_add_u64 v[130:131], s[38:39], 0, v[130:131]
	v_and_b32_e32 v0, 64, v136
	v_lshl_add_u64 v[130:131], s[46:47], 1, v[130:131]
	v_lshlrev_b32_e32 v0, 1, v0
	v_lshl_add_u64 v[138:139], v[130:131], 0, v[0:1]
	v_lshlrev_b32_e32 v0, 4, v136
	v_and_b32_e32 v0, 0x70, v0
	v_bfe_u32 v140, v136, 3, 3
	v_or_b32_e32 v130, v137, v0
	s_waitcnt lgkmcnt(0)
	v_mad_u32_u24 v137, v140, s4, v130
	ds_read_b128 v[66:69], v137
	ds_read_b128 v[70:73], v137 offset:1152
	ds_read_b128 v[74:77], v137 offset:2304
	ds_read_b128 v[78:81], v137 offset:3456
	ds_read_b128 v[82:85], v137 offset:4608
	ds_read_b128 v[86:89], v137 offset:5760
	ds_read_b128 v[90:93], v137 offset:6912
	ds_read_b128 v[94:97], v137 offset:8064
	ds_read_b128 v[98:101], v137 offset:9216
	ds_read_b128 v[102:105], v137 offset:10368
	ds_read_b128 v[106:109], v137 offset:11520
	ds_read_b128 v[110:113], v137 offset:12672
	ds_read_b128 v[114:117], v137 offset:13824
	ds_read_b128 v[118:121], v137 offset:14976
	ds_read_b128 v[122:125], v137 offset:16128
	ds_read_b128 v[126:129], v137 offset:17280
	v_lshl_add_u64 v[138:139], v[138:139], 0, v[0:1]
	v_lshlrev_b32_e32 v0, 11, v140
	v_lshl_add_u64 v[140:141], v[138:139], 0, v[0:1]
	s_mov_b64 s[50:51], 0
	s_waitcnt lgkmcnt(15)
	global_store_dwordx4 v[140:141], v[66:69], off
	v_or_b32_e32 v140, 0x4000, v0
	v_mov_b32_e32 v141, v1
	v_lshl_add_u64 v[140:141], v[138:139], 0, v[140:141]
	s_waitcnt lgkmcnt(14)
	global_store_dwordx4 v[140:141], v[70:73], off
	v_or_b32_e32 v140, 0x8000, v0
	v_mov_b32_e32 v141, v1
	v_lshl_add_u64 v[140:141], v[138:139], 0, v[140:141]
	s_waitcnt lgkmcnt(13)
	global_store_dwordx4 v[140:141], v[74:77], off
	v_or_b32_e32 v140, 0xc000, v0
	v_mov_b32_e32 v141, v1
	v_lshl_add_u64 v[140:141], v[138:139], 0, v[140:141]
	s_waitcnt lgkmcnt(12)
	global_store_dwordx4 v[140:141], v[78:81], off
	v_or_b32_e32 v140, 0x10000, v0
	v_mov_b32_e32 v141, v1
	v_lshl_add_u64 v[140:141], v[138:139], 0, v[140:141]
	s_waitcnt lgkmcnt(11)
	global_store_dwordx4 v[140:141], v[82:85], off
	v_or_b32_e32 v140, 0x14000, v0
	v_mov_b32_e32 v141, v1
	v_lshl_add_u64 v[140:141], v[138:139], 0, v[140:141]
	s_waitcnt lgkmcnt(10)
	global_store_dwordx4 v[140:141], v[86:89], off
	v_or_b32_e32 v140, 0x18000, v0
	v_mov_b32_e32 v141, v1
	v_lshl_add_u64 v[140:141], v[138:139], 0, v[140:141]
	s_waitcnt lgkmcnt(9)
	global_store_dwordx4 v[140:141], v[90:93], off
	v_or_b32_e32 v140, 0x1c000, v0
	v_mov_b32_e32 v141, v1
	v_lshl_add_u64 v[140:141], v[138:139], 0, v[140:141]
	s_waitcnt lgkmcnt(8)
	global_store_dwordx4 v[140:141], v[94:97], off
	v_or_b32_e32 v140, 0x20000, v0
	v_mov_b32_e32 v141, v1
	v_lshl_add_u64 v[140:141], v[138:139], 0, v[140:141]
	s_waitcnt lgkmcnt(7)
	global_store_dwordx4 v[140:141], v[98:101], off
	v_or_b32_e32 v140, 0x24000, v0
	v_mov_b32_e32 v141, v1
	v_lshl_add_u64 v[140:141], v[138:139], 0, v[140:141]
	s_waitcnt lgkmcnt(6)
	global_store_dwordx4 v[140:141], v[102:105], off
	v_or_b32_e32 v140, 0x28000, v0
	v_mov_b32_e32 v141, v1
	v_lshl_add_u64 v[140:141], v[138:139], 0, v[140:141]
	s_waitcnt lgkmcnt(5)
	global_store_dwordx4 v[140:141], v[106:109], off
	v_or_b32_e32 v140, 0x2c000, v0
	v_mov_b32_e32 v141, v1
	v_lshl_add_u64 v[140:141], v[138:139], 0, v[140:141]
	s_waitcnt lgkmcnt(4)
	global_store_dwordx4 v[140:141], v[110:113], off
	v_or_b32_e32 v140, 0x30000, v0
	v_mov_b32_e32 v141, v1
	v_lshl_add_u64 v[140:141], v[138:139], 0, v[140:141]
	s_waitcnt lgkmcnt(3)
	global_store_dwordx4 v[140:141], v[114:117], off
	v_or_b32_e32 v140, 0x34000, v0
	v_mov_b32_e32 v141, v1
	v_lshl_add_u64 v[140:141], v[138:139], 0, v[140:141]
	s_waitcnt lgkmcnt(2)
	global_store_dwordx4 v[140:141], v[118:121], off
	v_or_b32_e32 v140, 0x38000, v0
	v_mov_b32_e32 v141, v1
	v_lshl_add_u64 v[140:141], v[138:139], 0, v[140:141]
	v_or_b32_e32 v0, 0x3c000, v0
	s_waitcnt lgkmcnt(1)
	global_store_dwordx4 v[140:141], v[122:125], off
	v_lshl_add_u64 v[138:139], v[138:139], 0, v[0:1]
	s_waitcnt lgkmcnt(0)
	global_store_dwordx4 v[138:139], v[126:129], off
	s_waitcnt lgkmcnt(0)
	s_barrier
